# prompt attention blocks: the 8 query blocks of one (batch, head) mapped to workgroups of the same XCD (shared K / V^T reads)
# speedup vs baseline: 1.0038x; 1.0038x over previous
.LBB0_799:
	s_or_b64 exec, exec, s[6:7]
	v_mov_b32_e32 v144, v164
	s_waitcnt lgkmcnt(0)
	s_barrier
	s_add_u32 s6, s34, 0x27600000
	s_addc_u32 s7, s35, 0
	v_mov_b32_e32 v8, v164
	s_and_b32 s99, s2, 7
	s_lshr_b32 s98, s2, 6
	s_lshl_b32 s98, s98, 3
	s_add_i32 s99, s99, s98
	s_lshl_b32 s99, s99, 3
	s_bfe_u32 s98, s2, 0x30003
	s_add_i32 s99, s99, s98
	s_cmpk_lt_i32 s2, 0x80
	s_cselect_b64 s[8:9], -1, 0
	s_cmpk_gt_i32 s2, 0x7f
	v_readfirstlane_b32 s53, v8
	s_cbranch_scc1 .LBB0_825
	v_lshlrev_b32_e32 v0, 4, v8
	v_add_u32_e32 v1, 0x2000, v0
	v_ashrrev_i32_e32 v2, 31, v1
	v_lshrrev_b32_e32 v2, 22, v2
	v_add_u32_e32 v2, v1, v2
	v_ashrrev_i32_e32 v127, 10, v2
	v_mul_i32_i24_e32 v2, 0x400, v127
	v_sub_u32_e32 v1, v1, v2
	v_lshrrev_b32_e32 v2, 4, v1
	v_bitop3_b32 v1, v2, v1, 32 bitop3:0x6c
	v_ashrrev_i32_e32 v2, 31, v1
	v_lshrrev_b32_e32 v2, 26, v2
	v_add_u32_e32 v2, v1, v2
	v_lshlrev_b32_e32 v3, 3, v127
	v_ashrrev_i32_e32 v136, 6, v2
	v_and_b32_e32 v3, -16, v3
	v_add_u32_e32 v3, v136, v3
	v_and_b32_e32 v4, 3, v136
	s_mov_b32 s10, 0xfffe0
	v_lshrrev_b32_e32 v5, 2, v3
	v_lshlrev_b32_e32 v6, 1, v3
	v_and_b32_e32 v2, 0xc0, v2
	v_and_or_b32 v4, v3, s10, v4
	v_and_b32_e32 v5, 4, v5
	v_and_b32_e32 v6, 24, v6
	v_sub_u32_e32 v1, v1, v2
	v_mov_b32_e32 v2, 1
	v_or3_b32 v4, v4, v5, v6
	v_lshlrev_b32_e32 v5, 5, v127
	v_ashrrev_i16_sdwa v1, v2, sext(v1) dst_sel:DWORD dst_unused:UNUSED_PAD src0_sel:DWORD src1_sel:BYTE_0
	v_and_b32_e32 v5, 32, v5
	v_bfe_i32 v137, v1, 0, 16
	v_add_lshl_u32 v1, v5, v137, 1
	v_lshl_add_u32 v130, v4, 12, v1
	v_lshl_add_u32 v132, v3, 12, v1
	v_bfe_i32 v1, v8, 27, 1
	v_lshrrev_b32_e32 v1, 22, v1
	v_add_u32_e32 v1, v0, v1
	v_and_b32_e32 v1, 0xfffffc00, v1
	v_sub_u32_e32 v0, v0, v1
	v_lshrrev_b32_e32 v1, 4, v0
	v_ashrrev_i32_e32 v3, 31, v8
	v_bitop3_b32 v0, v1, v0, 32 bitop3:0x6c
	v_lshrrev_b32_e32 v3, 26, v3
	v_ashrrev_i32_e32 v1, 31, v0
	v_add_u32_e32 v3, v8, v3
	v_lshrrev_b32_e32 v1, 26, v1
	v_ashrrev_i32_e32 v139, 6, v3
	v_add_u32_e32 v1, v0, v1
	v_lshlrev_b32_e32 v3, 3, v139
	v_ashrrev_i32_e32 v138, 6, v1
	v_and_b32_e32 v3, -16, v3
	v_add_u32_e32 v3, v138, v3
	v_and_b32_e32 v4, 3, v138
	v_and_or_b32 v4, v3, s10, v4
	s_ashr_i32 s29, s99, 5
	s_lshl_b32 s10, s99, 8
	s_lshl_b32 s47, s29, 11
	s_and_b32 s25, s10, 0x700
	s_or_b32 s10, s47, s25
	s_ashr_i32 s14, s53, 6
	s_bfe_u32 s19, s99, 0x20003
	s_ashr_i32 s11, s10, 31
	s_ashr_i32 s3, s53, 8
	s_lshl_b32 s46, s14, 10
	s_lshl_b32 s44, s19, 10
	s_lshl_b64 s[10:11], s[10:11], 12
	s_add_u32 s10, s34, s10
	s_addc_u32 s11, s35, s11
	s_add_u32 s15, s10, s44
	s_addc_u32 s45, s11, 0
	s_add_u32 s10, s15, 0x24a00000
	s_addc_u32 s11, s45, 0
	s_lshl_b32 s12, s29, 8
	s_ashr_i32 s13, s12, 31
	s_lshl_b64 s[12:13], s[12:13], 12
	s_add_u32 s12, s34, s12
	v_lshrrev_b32_e32 v5, 2, v3
	v_lshlrev_b32_e32 v6, 1, v3
	v_and_b32_e32 v1, 0xc0, v1
	s_addc_u32 s13, s35, s13
	v_and_b32_e32 v5, 4, v5
	v_and_b32_e32 v6, 24, v6
	v_sub_u32_e32 v0, v0, v1
	s_add_u32 s40, s12, s44
	v_or3_b32 v4, v4, v5, v6
	v_lshlrev_b32_e32 v5, 5, v139
	v_ashrrev_i16_sdwa v0, v2, sext(v0) dst_sel:DWORD dst_unused:UNUSED_PAD src0_sel:DWORD src1_sel:BYTE_0
	s_addc_u32 s41, s13, 0
	v_and_b32_e32 v5, 32, v5
	v_bfe_i32 v140, v0, 0, 16
	s_add_u32 s12, s40, 0x26e00000
	v_add_lshl_u32 v0, v5, v140, 1
	s_addc_u32 s13, s41, 0
	s_add_i32 s54, s46, 0
	v_lshl_add_u32 v128, v4, 12, v0
	s_add_i32 m0, s54, 0x10000
	v_lshl_add_u32 v134, v3, 12, v0
	global_load_lds_dwordx4 v128, s[12:13]
	s_add_i32 m0, s54, 0x12000
	s_add_u32 s40, s40, 0x26e80000
	global_load_lds_dwordx4 v130, s[12:13]
	s_addc_u32 s41, s41, 0
	s_add_i32 m0, s54, 0x14000
	s_add_i32 s55, s54, 0x2000
	global_load_lds_dwordx4 v128, s[40:41]
	s_add_i32 m0, s54, 0x16000
	v_mov_b32_e32 v129, 0
	global_load_lds_dwordx4 v130, s[40:41]
	s_mov_b32 m0, s54
	s_add_u32 s40, s15, 0x24a80000
	global_load_lds_dwordx4 v134, s[10:11]
	s_mov_b32 m0, s55
	s_addc_u32 s41, s45, 0
	s_add_i32 s56, s54, 0x4000
	global_load_lds_dwordx4 v132, s[10:11]
	s_mov_b32 m0, s56
	s_add_i32 s57, s54, 0x6000
	global_load_lds_dwordx4 v134, s[40:41]
	s_mov_b32 m0, s57
	v_mov_b32_e32 v131, v129
	global_load_lds_dwordx4 v132, s[40:41]
	v_mov_b32_e32 v135, v129
	v_mov_b32_e32 v133, v129
	s_mov_b32 s58, 8
	s_mov_b32 s45, 0
	v_lshl_add_u64 v[6:7], s[12:13], 0, v[128:129]
	v_lshl_add_u64 v[4:5], s[12:13], 0, v[130:131]
	v_lshl_add_u64 v[2:3], s[10:11], 0, v[134:135]
	s_cmp_lg_u32 s3, 1
	v_lshl_add_u64 v[0:1], s[10:11], 0, v[132:133]
	s_cbranch_scc1 .LBB0_802
	s_barrier

.LBB0_825:
	s_waitcnt vmcnt(0)
	s_add_u32 s44, s34, 0x28600000
	v_mov_b32_e32 v10, v164
	s_waitcnt vmcnt(0) lgkmcnt(0)
	s_barrier
	s_addc_u32 s45, s35, 0
	s_andn2_b64 vcc, exec, s[8:9]
	v_readfirstlane_b32 s12, v10
	s_cbranch_vccnz .LBB0_841
	v_lshlrev_b32_e32 v0, 4, v10
	v_add_u32_e32 v1, 0x2000, v0
	v_ashrrev_i32_e32 v2, 31, v1
	v_lshrrev_b32_e32 v2, 22, v2
	v_add_u32_e32 v2, v1, v2
	v_ashrrev_i32_e32 v8, 10, v2
	v_mul_i32_i24_e32 v2, 0x400, v8
	v_sub_u32_e32 v1, v1, v2
	v_lshrrev_b32_e32 v2, 4, v1
	v_bitop3_b32 v1, v2, v1, 32 bitop3:0x6c
	v_ashrrev_i32_e32 v2, 31, v1
	v_lshrrev_b32_e32 v2, 26, v2
	v_add_u32_e32 v2, v1, v2
	v_lshlrev_b32_e32 v3, 3, v8
	v_ashrrev_i32_e32 v9, 6, v2
	v_and_b32_e32 v3, -16, v3
	v_add_u32_e32 v3, v9, v3
	v_and_b32_e32 v4, 3, v9
	s_mov_b32 s8, 0x7fffe0
	v_lshrrev_b32_e32 v5, 2, v3
	v_lshlrev_b32_e32 v6, 1, v3
	v_and_b32_e32 v2, 0xc0, v2
	v_and_or_b32 v4, v3, s8, v4
	v_and_b32_e32 v5, 4, v5
	v_and_b32_e32 v6, 24, v6
	v_sub_u32_e32 v1, v1, v2
	v_mov_b32_e32 v2, 1
	v_or3_b32 v4, v4, v5, v6
	v_lshlrev_b32_e32 v5, 5, v8
	v_ashrrev_i16_sdwa v1, v2, sext(v1) dst_sel:DWORD dst_unused:UNUSED_PAD src0_sel:DWORD src1_sel:BYTE_0
	v_and_b32_e32 v5, 32, v5
	v_bfe_i32 v11, v1, 0, 16
	v_add_lshl_u32 v1, v5, v11, 1
	v_lshl_add_u32 v128, v4, 9, v1
	v_lshl_add_u32 v130, v3, 9, v1
	v_bfe_i32 v1, v10, 27, 1
	v_lshrrev_b32_e32 v1, 22, v1
	v_add_u32_e32 v1, v0, v1
	v_and_b32_e32 v1, 0xfffffc00, v1
	v_sub_u32_e32 v0, v0, v1
	v_lshrrev_b32_e32 v1, 4, v0
	v_ashrrev_i32_e32 v3, 31, v10
	v_bitop3_b32 v0, v1, v0, 32 bitop3:0x6c
	v_lshrrev_b32_e32 v3, 26, v3
	v_ashrrev_i32_e32 v1, 31, v0
	v_add_u32_e32 v3, v10, v3
	v_lshrrev_b32_e32 v1, 26, v1
	v_ashrrev_i32_e32 v13, 6, v3
	s_add_u32 s14, s34, 0x27200000
	v_add_u32_e32 v1, v0, v1
	v_lshlrev_b32_e32 v3, 3, v13
	s_addc_u32 s15, s35, 0
	v_ashrrev_i32_e32 v12, 6, v1
	v_and_b32_e32 v3, -16, v3
	s_ashr_i32 s13, s99, 5
	s_bfe_u32 s19, s99, 0x20003
	v_add_u32_e32 v3, v12, v3
	v_and_b32_e32 v4, 3, v12
	s_lshl_b32 s46, s13, 13
	s_lshl_b32 s47, s19, 11
	s_lshl_b32 s9, s99, 8
	v_and_or_b32 v4, v3, s8, v4
	s_or_b32 s8, s47, s46
	s_and_b32 s49, s9, 0x700
	s_or_b32 s8, s8, s49
	s_ashr_i32 s10, s12, 6
	s_ashr_i32 s9, s8, 31
	s_ashr_i32 s11, s12, 8
	s_lshl_b32 s3, s10, 10
	s_lshl_b64 s[8:9], s[8:9], 9
	s_add_u32 s6, s6, s8
	s_addc_u32 s7, s7, s9
	s_lshl_b32 s40, s13, 11
	s_lshl_b32 s48, s19, 9
	v_lshrrev_b32_e32 v5, 2, v3
	v_lshlrev_b32_e32 v6, 1, v3
	v_and_b32_e32 v1, 0xc0, v1
	s_or_b32 s8, s48, s40
	v_and_b32_e32 v5, 4, v5
	v_and_b32_e32 v6, 24, v6
	v_sub_u32_e32 v0, v0, v1
	s_ashr_i32 s9, s8, 31
	v_or3_b32 v4, v4, v5, v6
	v_lshlrev_b32_e32 v5, 5, v13
	v_ashrrev_i16_sdwa v0, v2, sext(v0) dst_sel:DWORD dst_unused:UNUSED_PAD src0_sel:DWORD src1_sel:BYTE_0
	s_lshl_b64 s[8:9], s[8:9], 9
	v_and_b32_e32 v5, 32, v5
	v_bfe_i32 v14, v0, 0, 16
	s_add_u32 s50, s14, s8
	v_add_lshl_u32 v0, v5, v14, 1
	s_addc_u32 s51, s15, s9
	s_add_i32 s19, s3, 0
	v_lshl_add_u32 v132, v4, 9, v0
	s_add_i32 m0, s19, 0x10000
	v_lshl_add_u32 v134, v3, 9, v0
	global_load_lds_dwordx4 v132, s[50:51]
	s_add_i32 m0, s19, 0x12000
	s_add_u32 s8, s50, 0x10000
	global_load_lds_dwordx4 v128, s[50:51]
	s_addc_u32 s9, s51, 0
	s_add_i32 m0, s19, 0x14000
	s_add_i32 s25, s19, 0x2000
	global_load_lds_dwordx4 v132, s[8:9]
	s_add_i32 m0, s19, 0x16000
	v_mov_b32_e32 v133, 0
	global_load_lds_dwordx4 v128, s[8:9]
	s_mov_b32 m0, s19
	s_add_u32 s8, s6, 0x10000
	global_load_lds_dwordx4 v134, s[6:7]
	s_mov_b32 m0, s25
	s_addc_u32 s9, s7, 0
	s_add_i32 s29, s19, 0x4000
	global_load_lds_dwordx4 v130, s[6:7]
	s_mov_b32 m0, s29
	s_add_i32 s58, s19, 0x6000
	global_load_lds_dwordx4 v134, s[8:9]
	s_mov_b32 m0, s58
	v_mov_b32_e32 v129, v133
	global_load_lds_dwordx4 v130, s[8:9]
	v_mov_b32_e32 v135, v133
	v_mov_b32_e32 v131, v133
	s_cmp_eq_u32 s11, 1
	v_lshl_add_u64 v[6:7], s[50:51], 0, v[132:133]
	v_lshl_add_u64 v[4:5], s[50:51], 0, v[128:129]
	v_lshl_add_u64 v[0:1], s[6:7], 0, v[134:135]
	s_cselect_b64 s[8:9], -1, 0
	s_cmp_lg_u32 s11, 1
	v_lshl_add_u64 v[2:3], s[6:7], 0, v[130:131]
	s_cbranch_scc1 .LBB0_828
	s_barrier
